# v36: residual rows of row group 0 prefetched at the unit-loop header (before the K loop) into v234-v249, epilogue starts computing after only the gate-vector load
# baseline (speedup 1.0000x reference)
;   __device__ __forceinline__ void operator()(const f32x4 (&acc)[2][2][4][2], const Unit& u, int wr, int wc, int fr, int fq) const {
;     const int mr = (u.pm * 256 < ML) ? ((u.pm * 256) >> 11) : 32;
;     const float* gp = mod + (size_t)mr * 6144 + gate_off;
; #pragma unroll
;     for (int ai = 0; ai < 2; ++ai)
; #pragma unroll
;       for (int m = 0; m < 4; ++m) {
;         const int r = u.pm * 256 + ai * 128 + wr * 64 + m * 16 + fr;
;         const float* xi = (r < ML) ? xin_l + (size_t)r * 1024 : xin_c + (size_t)(r - ML) * 1024;
;         float* xo = (r < ML) ? xout_l + (size_t)r * 1024 : xout_c + (size_t)(r - ML) * 1024;
; #pragma unroll
;         for (int bj = 0; bj < 2; ++bj)
; #pragma unroll
;           for (int n = 0; n < 2; ++n) {
;             const int c = u.pn * 256 + bj * 128 + wc * 32 + n * 16 + 4 * fq;
;             const float4 g = *reinterpret_cast<const float4*>(gp + c);
;             const float4 x = *reinterpret_cast<const float4*>(xi + c);
;             const f32x4 v = acc[ai][bj][m][n];
;             *reinterpret_cast<float4*>(xo + c) = make_float4(x.x + g.x * v[0], x.y + g.y * v[1], x.z + g.z * v[2], x.w + g.w * v[3]);
;           }
;       }
;   }
.LBB0_1478:
	s_lshl_b64 s[18:19], s[18:19], 2
	s_add_u32 s18, s46, s18
	s_addc_u32 s19, s47, s19
	v_lshl_or_b32 v140, s49, 8, v144
	v_lshlrev_b32_e32 v140, 2, v140
	global_load_dwordx4 v[146:149], v140, s[18:19]
	global_load_dwordx4 v[150:153], v140, s[18:19] offset:64
	global_load_dwordx4 v[154:157], v140, s[18:19] offset:512
	global_load_dwordx4 v[158:161], v140, s[18:19] offset:576
	s_cmpk_lt_i32 s16, 0x100
	s_cselect_b32 s100, s41, s43
	s_cselect_b32 s101, s40, s42
	s_cselect_b32 s24, s74, s62
	s_cselect_b32 s25, s75, s63
	s_cselect_b32 s1, 0, 0x100
	s_sub_i32 s1, s16, s1
	s_lshl_b32 s1, s1, 20
	v_lshlrev_b32_e32 v141, 12, v1
	v_add3_u32 v141, v141, v140, s1
	v_add_u32_e32 v142, 0x10000, v141
	global_load_dwordx4 v[204:207], v142, s[100:101]
	global_load_dwordx4 v[208:211], v142, s[100:101] offset:64
	global_load_dwordx4 v[212:215], v142, s[100:101] offset:512
	global_load_dwordx4 v[216:219], v142, s[100:101] offset:576
	v_add_u32_e32 v143, 0x20000, v141
	global_load_dwordx4 v[220:223], v143, s[100:101]
	global_load_dwordx4 v[224:227], v143, s[100:101] offset:64
	global_load_dwordx4 v[228:231], v143, s[100:101] offset:512
	global_load_dwordx4 v[182:185], v143, s[100:101] offset:576
	v_add_u32_e32 v174, 0x30000, v141
	global_load_dwordx4 v[162:165], v174, s[100:101]
	global_load_dwordx4 v[166:169], v174, s[100:101] offset:64
	global_load_dwordx4 v[170:173], v174, s[100:101] offset:512
	global_load_dwordx4 v[200:203], v174, s[100:101] offset:576
	s_mov_b32 s49, s0
	s_mov_b32 s16, s10
	s_mov_b64 s[20:21], s[14:15]
	s_mov_b64 s[18:19], s[12:13]
	s_and_b64 vcc, exec, s[6:7]
	s_waitcnt vmcnt(12)
	v_pk_fma_f32 v[126:127], v[126:127], v[146:147], v[234:235]
	v_pk_fma_f32 v[128:129], v[128:129], v[148:149], v[236:237]
	v_pk_fma_f32 v[122:123], v[122:123], v[150:151], v[238:239]
	v_pk_fma_f32 v[124:125], v[124:125], v[152:153], v[240:241]
	v_pk_fma_f32 v[118:119], v[118:119], v[154:155], v[242:243]
	v_pk_fma_f32 v[120:121], v[120:121], v[156:157], v[244:245]
	v_pk_fma_f32 v[114:115], v[114:115], v[158:159], v[246:247]
	v_pk_fma_f32 v[116:117], v[116:117], v[160:161], v[248:249]
	global_store_dwordx4 v141, v[126:129], s[24:25]
	global_store_dwordx4 v141, v[122:125], s[24:25] offset:64
	global_store_dwordx4 v141, v[118:121], s[24:25] offset:512
	global_store_dwordx4 v141, v[114:117], s[24:25] offset:576
	v_add_u32_e32 v175, 0x80000, v141
	global_load_dwordx4 v[234:237], v175, s[100:101]
	global_load_dwordx4 v[238:241], v175, s[100:101] offset:64
	global_load_dwordx4 v[242:245], v175, s[100:101] offset:512
	global_load_dwordx4 v[246:249], v175, s[100:101] offset:576
	v_add_u32_e32 v232, 0x90000, v141
	global_load_dwordx4 v[126:129], v232, s[100:101]
	global_load_dwordx4 v[122:125], v232, s[100:101] offset:64
	global_load_dwordx4 v[118:121], v232, s[100:101] offset:512
	global_load_dwordx4 v[114:117], v232, s[100:101] offset:576
	s_waitcnt vmcnt(20)
	v_pk_fma_f32 v[110:111], v[110:111], v[146:147], v[204:205]
	v_pk_fma_f32 v[112:113], v[112:113], v[148:149], v[206:207]
	v_pk_fma_f32 v[106:107], v[106:107], v[150:151], v[208:209]
	v_pk_fma_f32 v[108:109], v[108:109], v[152:153], v[210:211]
	v_pk_fma_f32 v[102:103], v[102:103], v[154:155], v[212:213]
	v_pk_fma_f32 v[104:105], v[104:105], v[156:157], v[214:215]
	v_pk_fma_f32 v[98:99], v[98:99], v[158:159], v[216:217]
	v_pk_fma_f32 v[100:101], v[100:101], v[160:161], v[218:219]
	global_store_dwordx4 v142, v[110:113], s[24:25]
	global_store_dwordx4 v142, v[106:109], s[24:25] offset:64
	global_store_dwordx4 v142, v[102:105], s[24:25] offset:512
	global_store_dwordx4 v142, v[98:101], s[24:25] offset:576
	v_add_u32_e32 v233, 0xa0000, v141
	global_load_dwordx4 v[204:207], v233, s[100:101]
	global_load_dwordx4 v[208:211], v233, s[100:101] offset:64
	global_load_dwordx4 v[212:215], v233, s[100:101] offset:512
	global_load_dwordx4 v[216:219], v233, s[100:101] offset:576
	v_add_u32_e32 v142, 0xb0000, v141
	global_load_dwordx4 v[110:113], v142, s[100:101]
	global_load_dwordx4 v[106:109], v142, s[100:101] offset:64
	global_load_dwordx4 v[102:105], v142, s[100:101] offset:512
	global_load_dwordx4 v[98:101], v142, s[100:101] offset:576
	s_waitcnt vmcnt(28)
	v_pk_fma_f32 v[94:95], v[94:95], v[146:147], v[220:221]
	v_pk_fma_f32 v[96:97], v[96:97], v[148:149], v[222:223]
	v_pk_fma_f32 v[90:91], v[90:91], v[150:151], v[224:225]
	v_pk_fma_f32 v[92:93], v[92:93], v[152:153], v[226:227]
	v_pk_fma_f32 v[86:87], v[86:87], v[154:155], v[228:229]
	v_pk_fma_f32 v[88:89], v[88:89], v[156:157], v[230:231]
	v_pk_fma_f32 v[82:83], v[82:83], v[158:159], v[182:183]
	v_pk_fma_f32 v[84:85], v[84:85], v[160:161], v[184:185]
	global_store_dwordx4 v143, v[94:97], s[24:25]
	global_store_dwordx4 v143, v[90:93], s[24:25] offset:64
	global_store_dwordx4 v143, v[86:89], s[24:25] offset:512
	global_store_dwordx4 v143, v[82:85], s[24:25] offset:576
	s_waitcnt vmcnt(28)
;   __device__ __forceinline__ bool next(int i, Unit& u) const { if (i) return false; u = u0; return true; }
;   __device__ __forceinline__ bool next(int i, Unit& u) const {
;     const long L = (long)i * G + c;
;     if (L >= nwg) return false;
;     int wgid = (int)L;
;     { const int q = nwg / G_NXCD, r = nwg % G_NXCD, xcd = wgid % G_NXCD, off = wgid / G_NXCD; wgid = (xcd < r ? xcd * (q + 1) : r * (q + 1) + (xcd - r) * q) + off; }
;     const int nig = G_WGM * nN, gid = wgid / nig, fm = gid * G_WGM, gsz = (nM - fm) < G_WGM ? (nM - fm) : G_WGM;
;     u.pm = fm + ((wgid % nig) % gsz); u.pn = (wgid % nig) / gsz;
;     return true;
;   }
;   __device__ __forceinline__ void operator()(const f32x4 (&acc)[2][2][4][2], const Unit& u, int wr, int wc, int fr, int fq) const {
;     const int mr = (u.pm * 256 < ML) ? ((u.pm * 256) >> 11) : 32;
;     const float* gp = mod + (size_t)mr * 6144 + gate_off;
; #pragma unroll
;     for (int ai = 0; ai < 2; ++ai)
; #pragma unroll
;       for (int m = 0; m < 4; ++m) {
;         const int r = u.pm * 256 + ai * 128 + wr * 64 + m * 16 + fr;
;         const float* xi = (r < ML) ? xin_l + (size_t)r * 1024 : xin_c + (size_t)(r - ML) * 1024;
;         float* xo = (r < ML) ? xout_l + (size_t)r * 1024 : xout_c + (size_t)(r - ML) * 1024;
; #pragma unroll
;         for (int bj = 0; bj < 2; ++bj)
; #pragma unroll
;           for (int n = 0; n < 2; ++n) {
;             const int c = u.pn * 256 + bj * 128 + wc * 32 + n * 16 + 4 * fq;
;             const float4 g = *reinterpret_cast<const float4*>(gp + c);
;             const float4 x = *reinterpret_cast<const float4*>(xi + c);
;             const f32x4 v = acc[ai][bj][m][n];
;             *reinterpret_cast<float4*>(xo + c) = make_float4(x.x + g.x * v[0], x.y + g.y * v[1], x.z + g.z * v[2], x.w + g.w * v[3]);
;           }
;       }
;   }
	v_pk_fma_f32 v[78:79], v[78:79], v[146:147], v[162:163]
	v_pk_fma_f32 v[80:81], v[80:81], v[148:149], v[164:165]
	v_pk_fma_f32 v[74:75], v[74:75], v[150:151], v[166:167]
	v_pk_fma_f32 v[76:77], v[76:77], v[152:153], v[168:169]
	v_pk_fma_f32 v[70:71], v[70:71], v[154:155], v[170:171]
	v_pk_fma_f32 v[72:73], v[72:73], v[156:157], v[172:173]
	v_pk_fma_f32 v[66:67], v[66:67], v[158:159], v[200:201]
	v_pk_fma_f32 v[68:69], v[68:69], v[160:161], v[202:203]
	global_store_dwordx4 v174, v[78:81], s[24:25]
	global_store_dwordx4 v174, v[74:77], s[24:25] offset:64
	global_store_dwordx4 v174, v[70:73], s[24:25] offset:512
	global_store_dwordx4 v174, v[66:69], s[24:25] offset:576
	s_waitcnt vmcnt(24)
	v_pk_fma_f32 v[62:63], v[62:63], v[146:147], v[234:235]
	v_pk_fma_f32 v[64:65], v[64:65], v[148:149], v[236:237]
	v_pk_fma_f32 v[58:59], v[58:59], v[150:151], v[238:239]
	v_pk_fma_f32 v[60:61], v[60:61], v[152:153], v[240:241]
	v_pk_fma_f32 v[54:55], v[54:55], v[154:155], v[242:243]
	v_pk_fma_f32 v[56:57], v[56:57], v[156:157], v[244:245]
	v_pk_fma_f32 v[50:51], v[50:51], v[158:159], v[246:247]
	v_pk_fma_f32 v[52:53], v[52:53], v[160:161], v[248:249]
	global_store_dwordx4 v175, v[62:65], s[24:25]
	global_store_dwordx4 v175, v[58:61], s[24:25] offset:64
	global_store_dwordx4 v175, v[54:57], s[24:25] offset:512
	global_store_dwordx4 v175, v[50:53], s[24:25] offset:576
	s_waitcnt vmcnt(24)
	v_pk_fma_f32 v[46:47], v[46:47], v[146:147], v[126:127]
	v_pk_fma_f32 v[48:49], v[48:49], v[148:149], v[128:129]
	v_pk_fma_f32 v[42:43], v[42:43], v[150:151], v[122:123]
	v_pk_fma_f32 v[44:45], v[44:45], v[152:153], v[124:125]
	v_pk_fma_f32 v[38:39], v[38:39], v[154:155], v[118:119]
	v_pk_fma_f32 v[40:41], v[40:41], v[156:157], v[120:121]
	v_pk_fma_f32 v[34:35], v[34:35], v[158:159], v[114:115]
	v_pk_fma_f32 v[36:37], v[36:37], v[160:161], v[116:117]
	global_store_dwordx4 v232, v[46:49], s[24:25]
	global_store_dwordx4 v232, v[42:45], s[24:25] offset:64
	global_store_dwordx4 v232, v[38:41], s[24:25] offset:512
	global_store_dwordx4 v232, v[34:37], s[24:25] offset:576
	s_waitcnt vmcnt(20)
	v_pk_fma_f32 v[30:31], v[30:31], v[146:147], v[204:205]
	v_pk_fma_f32 v[32:33], v[32:33], v[148:149], v[206:207]
	v_pk_fma_f32 v[26:27], v[26:27], v[150:151], v[208:209]
	v_pk_fma_f32 v[28:29], v[28:29], v[152:153], v[210:211]
	v_pk_fma_f32 v[22:23], v[22:23], v[154:155], v[212:213]
	v_pk_fma_f32 v[24:25], v[24:25], v[156:157], v[214:215]
	v_pk_fma_f32 v[18:19], v[18:19], v[158:159], v[216:217]
	v_pk_fma_f32 v[20:21], v[20:21], v[160:161], v[218:219]
	global_store_dwordx4 v233, v[30:33], s[24:25]
	global_store_dwordx4 v233, v[26:29], s[24:25] offset:64
	global_store_dwordx4 v233, v[22:25], s[24:25] offset:512
	global_store_dwordx4 v233, v[18:21], s[24:25] offset:576
	s_waitcnt vmcnt(20)
	v_pk_fma_f32 v[14:15], v[14:15], v[146:147], v[110:111]
	v_pk_fma_f32 v[16:17], v[16:17], v[148:149], v[112:113]
	v_pk_fma_f32 v[10:11], v[10:11], v[150:151], v[106:107]
	v_pk_fma_f32 v[12:13], v[12:13], v[152:153], v[108:109]
	v_pk_fma_f32 v[6:7], v[6:7], v[154:155], v[102:103]
	v_pk_fma_f32 v[8:9], v[8:9], v[156:157], v[104:105]
	v_pk_fma_f32 v[2:3], v[2:3], v[158:159], v[98:99]
	v_pk_fma_f32 v[4:5], v[4:5], v[160:161], v[100:101]
	global_store_dwordx4 v142, v[14:17], s[24:25]
	global_store_dwordx4 v142, v[10:13], s[24:25] offset:64
	global_store_dwordx4 v142, v[6:9], s[24:25] offset:512
	global_store_dwordx4 v142, v[2:5], s[24:25] offset:576
	s_cbranch_vccnz .LBB0_1485
.LBB0_1479:
	s_cmpk_lt_i32 s16, 0x100
	s_cselect_b32 s100, s41, s43
	s_cselect_b32 s101, s40, s42
	s_cselect_b32 s1, 0, 0x100
	s_sub_i32 s1, s16, s1
	s_lshl_b32 s1, s1, 20
	v_lshl_or_b32 v250, s49, 8, v144
	v_lshlrev_b32_e32 v250, 2, v250
	v_lshlrev_b32_e32 v251, 12, v1
	v_add3_u32 v250, v251, v250, s1
	global_load_dwordx4 v[234:237], v250, s[100:101]
	global_load_dwordx4 v[238:241], v250, s[100:101] offset:64
	global_load_dwordx4 v[242:245], v250, s[100:101] offset:512
	global_load_dwordx4 v[246:249], v250, s[100:101] offset:576
	s_add_i32 s48, s48, 1
	v_readlane_b32 s1, v253, 4
	s_mul_i32 s1, s48, s1
	s_mul_hi_u32 s6, s48, s78
	s_add_i32 s6, s6, s1
	s_mul_i32 s1, s48, s78
	s_add_u32 s12, s1, s68
	v_readlane_b32 s1, v253, 2
	s_addc_u32 s13, s6, s1
	v_mov_b64_e32 v[2:3], s[8:9]
	v_cmp_ge_i64_e64 s[6:7], s[12:13], v[2:3]
	s_and_b64 vcc, exec, s[6:7]
	s_cbranch_vccnz .LBB0_1481
	s_ashr_i32 s0, s12, 31
	s_lshr_b32 s0, s0, 29
	s_add_i32 s0, s12, s0
	s_ashr_i32 s1, s0, 3
	s_and_b32 s0, s0, -8
	s_sub_i32 s0, s12, s0
	s_cmp_lt_i32 s0, 0
	s_cselect_b32 s10, s36, s35
	s_mul_i32 s0, s10, s0
	s_add_i32 s0, s0, s1
	s_ashr_i32 s1, s0, 31
	s_lshr_b32 s1, s1, 27
	s_add_i32 s1, s0, s1
	s_ashr_i32 s10, s1, 5
	s_lshl_b32 s10, s10, 3
	s_sub_i32 s11, s27, s10
	s_min_i32 s11, s11, 8
	s_abs_i32 s14, s11
	v_cvt_f32_u32_e32 v2, s14
	s_sub_i32 s22, 0, s14
	s_andn2_b32 s1, s1, 31
	s_sub_i32 s1, s0, s1
	v_rcp_iflag_f32_e32 v2, v2
	s_abs_i32 s0, s1
	s_xor_b32 s15, s1, s11
	s_ashr_i32 s15, s15, 31
	v_mul_f32_e32 v2, 0x4f7ffffe, v2
	v_cvt_u32_f32_e32 v2, v2
	s_nop 0
	v_readfirstlane_b32 s23, v2
	s_mul_i32 s22, s22, s23
	s_mul_hi_u32 s22, s23, s22
	s_add_i32 s23, s23, s22
	s_mul_hi_u32 s22, s0, s23
	s_mul_i32 s23, s22, s14
	s_sub_i32 s0, s0, s23
	s_add_i32 s24, s22, 1
	s_sub_i32 s23, s0, s14
	s_cmp_ge_u32 s0, s14
	s_cselect_b32 s22, s24, s22
	s_cselect_b32 s0, s23, s0
	s_add_i32 s23, s22, 1
	s_cmp_ge_u32 s0, s14
	s_cselect_b32 s0, s23, s22
	s_xor_b32 s0, s0, s15
	s_sub_i32 s0, s0, s15
	s_mul_i32 s11, s0, s11
	s_sub_i32 s1, s1, s11
	s_add_i32 s10, s1, s10

;   __device__ __forceinline__ void operator()(const f32x4 (&acc)[2][2][4][2], const Unit& u, int wr, int wc, int fr, int fq) const {
;     const int mr = (u.pm * 256 < ML) ? ((u.pm * 256) >> 11) : 32;
;     const float* gp = mod + (size_t)mr * 6144 + gate_off;
; #pragma unroll
;     for (int ai = 0; ai < 2; ++ai)
; #pragma unroll
;       for (int m = 0; m < 4; ++m) {
;         const int r = u.pm * 256 + ai * 128 + wr * 64 + m * 16 + fr;
;         const float* xi = (r < ML) ? xin_l + (size_t)r * 1024 : xin_c + (size_t)(r - ML) * 1024;
;         float* xo = (r < ML) ? xout_l + (size_t)r * 1024 : xout_c + (size_t)(r - ML) * 1024;
; #pragma unroll
;         for (int bj = 0; bj < 2; ++bj)
; #pragma unroll
;           for (int n = 0; n < 2; ++n) {
;             const int c = u.pn * 256 + bj * 128 + wc * 32 + n * 16 + 4 * fq;
;             const float4 g = *reinterpret_cast<const float4*>(gp + c);
;             const float4 x = *reinterpret_cast<const float4*>(xi + c);
;             const f32x4 v = acc[ai][bj][m][n];
;             *reinterpret_cast<float4*>(xo + c) = make_float4(x.x + g.x * v[0], x.y + g.y * v[1], x.z + g.z * v[2], x.w + g.w * v[3]);
;           }
;       }
;   }
.LBB0_1665:
	s_lshl_b64 s[10:11], s[10:11], 2
	s_add_u32 s10, s30, s10
	s_addc_u32 s11, s31, s11
	v_lshl_or_b32 v140, s38, 8, v144
	v_lshlrev_b32_e32 v140, 2, v140
	global_load_dwordx4 v[146:149], v140, s[10:11]
	global_load_dwordx4 v[150:153], v140, s[10:11] offset:64
	global_load_dwordx4 v[154:157], v140, s[10:11] offset:512
	global_load_dwordx4 v[158:161], v140, s[10:11] offset:576
	s_cmpk_lt_i32 s37, 0x100
	s_cselect_b64 s[100:101], s[74:75], s[62:63]
	s_cselect_b32 s10, 0, 0x100
	s_sub_i32 s10, s37, s10
	s_lshl_b32 s10, s10, 20
	v_lshlrev_b32_e32 v141, 12, v1
	v_add3_u32 v141, v141, v140, s10
	v_add_u32_e32 v142, 0x10000, v141
	global_load_dwordx4 v[204:207], v142, s[100:101]
	global_load_dwordx4 v[208:211], v142, s[100:101] offset:64
	global_load_dwordx4 v[212:215], v142, s[100:101] offset:512
	global_load_dwordx4 v[216:219], v142, s[100:101] offset:576
	v_add_u32_e32 v143, 0x20000, v141
	global_load_dwordx4 v[220:223], v143, s[100:101]
	global_load_dwordx4 v[224:227], v143, s[100:101] offset:64
	global_load_dwordx4 v[228:231], v143, s[100:101] offset:512
	global_load_dwordx4 v[182:185], v143, s[100:101] offset:576
	v_add_u32_e32 v174, 0x30000, v141
	global_load_dwordx4 v[162:165], v174, s[100:101]
	global_load_dwordx4 v[166:169], v174, s[100:101] offset:64
	global_load_dwordx4 v[170:173], v174, s[100:101] offset:512
	global_load_dwordx4 v[200:203], v174, s[100:101] offset:576
	v_readlane_b32 s40, v253, 12
	v_readlane_b32 s41, v253, 13
	v_readlane_b32 s44, v253, 16
	v_readlane_b32 s45, v253, 17
	v_readlane_b32 s52, v253, 24
	v_readlane_b32 s53, v253, 25
	v_readlane_b32 s54, v253, 26
	v_readlane_b32 s55, v253, 27
	v_readlane_b32 s42, v253, 14
	v_readlane_b32 s43, v253, 15
	v_readlane_b32 s46, v253, 18
	v_readlane_b32 s47, v253, 19
	v_readlane_b32 s48, v253, 20
	v_readlane_b32 s49, v253, 21
	v_readlane_b32 s50, v253, 22
	v_readlane_b32 s51, v253, 23
	s_mov_b32 s38, s35
	s_mov_b32 s37, s36
	s_mov_b64 s[12:13], s[0:1]
	s_and_b64 vcc, exec, s[4:5]
	s_waitcnt vmcnt(12)
	v_pk_fma_f32 v[126:127], v[126:127], v[146:147], v[234:235]
	v_pk_fma_f32 v[128:129], v[128:129], v[148:149], v[236:237]
	v_pk_fma_f32 v[122:123], v[122:123], v[150:151], v[238:239]
	v_pk_fma_f32 v[124:125], v[124:125], v[152:153], v[240:241]
	v_pk_fma_f32 v[118:119], v[118:119], v[154:155], v[242:243]
	v_pk_fma_f32 v[120:121], v[120:121], v[156:157], v[244:245]
	v_pk_fma_f32 v[114:115], v[114:115], v[158:159], v[246:247]
	v_pk_fma_f32 v[116:117], v[116:117], v[160:161], v[248:249]
	global_store_dwordx4 v141, v[126:129], s[100:101]
	global_store_dwordx4 v141, v[122:125], s[100:101] offset:64
	global_store_dwordx4 v141, v[118:121], s[100:101] offset:512
	global_store_dwordx4 v141, v[114:117], s[100:101] offset:576
	v_add_u32_e32 v175, 0x80000, v141
	global_load_dwordx4 v[234:237], v175, s[100:101]
	global_load_dwordx4 v[238:241], v175, s[100:101] offset:64
	global_load_dwordx4 v[242:245], v175, s[100:101] offset:512
	global_load_dwordx4 v[246:249], v175, s[100:101] offset:576
	v_add_u32_e32 v232, 0x90000, v141
	global_load_dwordx4 v[126:129], v232, s[100:101]
	global_load_dwordx4 v[122:125], v232, s[100:101] offset:64
	global_load_dwordx4 v[118:121], v232, s[100:101] offset:512
	global_load_dwordx4 v[114:117], v232, s[100:101] offset:576
	s_waitcnt vmcnt(20)
	v_pk_fma_f32 v[110:111], v[110:111], v[146:147], v[204:205]
	v_pk_fma_f32 v[112:113], v[112:113], v[148:149], v[206:207]
	v_pk_fma_f32 v[106:107], v[106:107], v[150:151], v[208:209]
	v_pk_fma_f32 v[108:109], v[108:109], v[152:153], v[210:211]
	v_pk_fma_f32 v[102:103], v[102:103], v[154:155], v[212:213]
	v_pk_fma_f32 v[104:105], v[104:105], v[156:157], v[214:215]
	v_pk_fma_f32 v[98:99], v[98:99], v[158:159], v[216:217]
	v_pk_fma_f32 v[100:101], v[100:101], v[160:161], v[218:219]
	global_store_dwordx4 v142, v[110:113], s[100:101]
	global_store_dwordx4 v142, v[106:109], s[100:101] offset:64
	global_store_dwordx4 v142, v[102:105], s[100:101] offset:512
	global_store_dwordx4 v142, v[98:101], s[100:101] offset:576
	v_add_u32_e32 v233, 0xa0000, v141
	global_load_dwordx4 v[204:207], v233, s[100:101]
	global_load_dwordx4 v[208:211], v233, s[100:101] offset:64
	global_load_dwordx4 v[212:215], v233, s[100:101] offset:512
	global_load_dwordx4 v[216:219], v233, s[100:101] offset:576
	v_add_u32_e32 v142, 0xb0000, v141
	global_load_dwordx4 v[110:113], v142, s[100:101]
	global_load_dwordx4 v[106:109], v142, s[100:101] offset:64
	global_load_dwordx4 v[102:105], v142, s[100:101] offset:512
	global_load_dwordx4 v[98:101], v142, s[100:101] offset:576
	s_waitcnt vmcnt(28)
	v_pk_fma_f32 v[94:95], v[94:95], v[146:147], v[220:221]
	v_pk_fma_f32 v[96:97], v[96:97], v[148:149], v[222:223]
	v_pk_fma_f32 v[90:91], v[90:91], v[150:151], v[224:225]
	v_pk_fma_f32 v[92:93], v[92:93], v[152:153], v[226:227]
	v_pk_fma_f32 v[86:87], v[86:87], v[154:155], v[228:229]
	v_pk_fma_f32 v[88:89], v[88:89], v[156:157], v[230:231]
	v_pk_fma_f32 v[82:83], v[82:83], v[158:159], v[182:183]
	v_pk_fma_f32 v[84:85], v[84:85], v[160:161], v[184:185]
	global_store_dwordx4 v143, v[94:97], s[100:101]
	global_store_dwordx4 v143, v[90:93], s[100:101] offset:64
	global_store_dwordx4 v143, v[86:89], s[100:101] offset:512
	global_store_dwordx4 v143, v[82:85], s[100:101] offset:576
	s_waitcnt vmcnt(28)
;   __device__ __forceinline__ bool next(int i, Unit& u) const { if (i) return false; u = u0; return true; }
;   __device__ __forceinline__ bool next(int i, Unit& u) const {
;     const long L = (long)i * G + c;
;     if (L >= nwg) return false;
;     int wgid = (int)L;
;     { const int q = nwg / G_NXCD, r = nwg % G_NXCD, xcd = wgid % G_NXCD, off = wgid / G_NXCD; wgid = (xcd < r ? xcd * (q + 1) : r * (q + 1) + (xcd - r) * q) + off; }
;     const int nig = G_WGM * nN, gid = wgid / nig, fm = gid * G_WGM, gsz = (nM - fm) < G_WGM ? (nM - fm) : G_WGM;
;     u.pm = fm + ((wgid % nig) % gsz); u.pn = (wgid % nig) / gsz;
;     return true;
;   }
;   __device__ __forceinline__ void operator()(const f32x4 (&acc)[2][2][4][2], const Unit& u, int wr, int wc, int fr, int fq) const {
;     const int mr = (u.pm * 256 < ML) ? ((u.pm * 256) >> 11) : 32;
;     const float* gp = mod + (size_t)mr * 6144 + gate_off;
; #pragma unroll
;     for (int ai = 0; ai < 2; ++ai)
; #pragma unroll
;       for (int m = 0; m < 4; ++m) {
;         const int r = u.pm * 256 + ai * 128 + wr * 64 + m * 16 + fr;
;         const float* xi = (r < ML) ? xin_l + (size_t)r * 1024 : xin_c + (size_t)(r - ML) * 1024;
;         float* xo = (r < ML) ? xout_l + (size_t)r * 1024 : xout_c + (size_t)(r - ML) * 1024;
; #pragma unroll
;         for (int bj = 0; bj < 2; ++bj)
; #pragma unroll
;           for (int n = 0; n < 2; ++n) {
;             const int c = u.pn * 256 + bj * 128 + wc * 32 + n * 16 + 4 * fq;
;             const float4 g = *reinterpret_cast<const float4*>(gp + c);
;             const float4 x = *reinterpret_cast<const float4*>(xi + c);
;             const f32x4 v = acc[ai][bj][m][n];
;             *reinterpret_cast<float4*>(xo + c) = make_float4(x.x + g.x * v[0], x.y + g.y * v[1], x.z + g.z * v[2], x.w + g.w * v[3]);
;           }
;       }
;   }
	v_pk_fma_f32 v[78:79], v[78:79], v[146:147], v[162:163]
	v_pk_fma_f32 v[80:81], v[80:81], v[148:149], v[164:165]
	v_pk_fma_f32 v[74:75], v[74:75], v[150:151], v[166:167]
	v_pk_fma_f32 v[76:77], v[76:77], v[152:153], v[168:169]
	v_pk_fma_f32 v[70:71], v[70:71], v[154:155], v[170:171]
	v_pk_fma_f32 v[72:73], v[72:73], v[156:157], v[172:173]
	v_pk_fma_f32 v[66:67], v[66:67], v[158:159], v[200:201]
	v_pk_fma_f32 v[68:69], v[68:69], v[160:161], v[202:203]
	global_store_dwordx4 v174, v[78:81], s[100:101]
	global_store_dwordx4 v174, v[74:77], s[100:101] offset:64
	global_store_dwordx4 v174, v[70:73], s[100:101] offset:512
	global_store_dwordx4 v174, v[66:69], s[100:101] offset:576
	s_waitcnt vmcnt(24)
	v_pk_fma_f32 v[62:63], v[62:63], v[146:147], v[234:235]
	v_pk_fma_f32 v[64:65], v[64:65], v[148:149], v[236:237]
	v_pk_fma_f32 v[58:59], v[58:59], v[150:151], v[238:239]
	v_pk_fma_f32 v[60:61], v[60:61], v[152:153], v[240:241]
	v_pk_fma_f32 v[54:55], v[54:55], v[154:155], v[242:243]
	v_pk_fma_f32 v[56:57], v[56:57], v[156:157], v[244:245]
	v_pk_fma_f32 v[50:51], v[50:51], v[158:159], v[246:247]
	v_pk_fma_f32 v[52:53], v[52:53], v[160:161], v[248:249]
	global_store_dwordx4 v175, v[62:65], s[100:101]
	global_store_dwordx4 v175, v[58:61], s[100:101] offset:64
	global_store_dwordx4 v175, v[54:57], s[100:101] offset:512
	global_store_dwordx4 v175, v[50:53], s[100:101] offset:576
	s_waitcnt vmcnt(24)
	v_pk_fma_f32 v[46:47], v[46:47], v[146:147], v[126:127]
	v_pk_fma_f32 v[48:49], v[48:49], v[148:149], v[128:129]
	v_pk_fma_f32 v[42:43], v[42:43], v[150:151], v[122:123]
	v_pk_fma_f32 v[44:45], v[44:45], v[152:153], v[124:125]
	v_pk_fma_f32 v[38:39], v[38:39], v[154:155], v[118:119]
	v_pk_fma_f32 v[40:41], v[40:41], v[156:157], v[120:121]
	v_pk_fma_f32 v[34:35], v[34:35], v[158:159], v[114:115]
	v_pk_fma_f32 v[36:37], v[36:37], v[160:161], v[116:117]
	global_store_dwordx4 v232, v[46:49], s[100:101]
	global_store_dwordx4 v232, v[42:45], s[100:101] offset:64
	global_store_dwordx4 v232, v[38:41], s[100:101] offset:512
	global_store_dwordx4 v232, v[34:37], s[100:101] offset:576
	s_waitcnt vmcnt(20)
	v_pk_fma_f32 v[30:31], v[30:31], v[146:147], v[204:205]
	v_pk_fma_f32 v[32:33], v[32:33], v[148:149], v[206:207]
	v_pk_fma_f32 v[26:27], v[26:27], v[150:151], v[208:209]
	v_pk_fma_f32 v[28:29], v[28:29], v[152:153], v[210:211]
	v_pk_fma_f32 v[22:23], v[22:23], v[154:155], v[212:213]
	v_pk_fma_f32 v[24:25], v[24:25], v[156:157], v[214:215]
	v_pk_fma_f32 v[18:19], v[18:19], v[158:159], v[216:217]
	v_pk_fma_f32 v[20:21], v[20:21], v[160:161], v[218:219]
	global_store_dwordx4 v233, v[30:33], s[100:101]
	global_store_dwordx4 v233, v[26:29], s[100:101] offset:64
	global_store_dwordx4 v233, v[22:25], s[100:101] offset:512
	global_store_dwordx4 v233, v[18:21], s[100:101] offset:576
	s_waitcnt vmcnt(20)
	v_pk_fma_f32 v[14:15], v[14:15], v[146:147], v[110:111]
	v_pk_fma_f32 v[16:17], v[16:17], v[148:149], v[112:113]
	v_pk_fma_f32 v[10:11], v[10:11], v[150:151], v[106:107]
	v_pk_fma_f32 v[12:13], v[12:13], v[152:153], v[108:109]
	v_pk_fma_f32 v[6:7], v[6:7], v[154:155], v[102:103]
	v_pk_fma_f32 v[8:9], v[8:9], v[156:157], v[104:105]
	v_pk_fma_f32 v[2:3], v[2:3], v[158:159], v[98:99]
	v_pk_fma_f32 v[4:5], v[4:5], v[160:161], v[100:101]
	global_store_dwordx4 v142, v[14:17], s[100:101]
	global_store_dwordx4 v142, v[10:13], s[100:101] offset:64
	global_store_dwordx4 v142, v[6:9], s[100:101] offset:512
	global_store_dwordx4 v142, v[2:5], s[100:101] offset:576
	s_mov_b64 s[10:11], s[6:7]
	s_cbranch_vccnz .LBB0_1676
.LBB0_1666:
	s_cmpk_lt_i32 s37, 0x100
	s_cselect_b64 s[100:101], s[74:75], s[62:63]
	s_cselect_b32 s1, 0, 0x100
	s_sub_i32 s1, s37, s1
	s_lshl_b32 s1, s1, 20
	v_lshl_or_b32 v250, s38, 8, v144
	v_lshlrev_b32_e32 v250, 2, v250
	v_lshlrev_b32_e32 v251, 12, v1
	v_add3_u32 v250, v251, v250, s1
	global_load_dwordx4 v[234:237], v250, s[100:101]
	global_load_dwordx4 v[238:241], v250, s[100:101] offset:64
	global_load_dwordx4 v[242:245], v250, s[100:101] offset:512
	global_load_dwordx4 v[246:249], v250, s[100:101] offset:576
	s_add_i32 s34, s34, 1
	v_readlane_b32 s0, v253, 4
	s_mul_i32 s0, s34, s0
	s_mul_hi_u32 s1, s34, s78
	s_add_i32 s1, s1, s0
	s_mul_i32 s0, s34, s78
	s_add_u32 s0, s0, s68
	v_readlane_b32 s4, v253, 2
	s_addc_u32 s1, s1, s4
	v_mov_b64_e32 v[2:3], s[8:9]
	v_cmp_ge_i64_e64 s[4:5], s[0:1], v[2:3]
	v_cmp_lt_i64_e64 s[6:7], s[0:1], v[2:3]
	s_and_b64 vcc, exec, s[4:5]
	s_cbranch_vccnz .LBB0_1668
	s_ashr_i32 s1, s0, 31
	s_lshr_b32 s1, s1, 29
	s_add_i32 s1, s0, s1
	s_ashr_i32 s14, s1, 3
	s_and_b32 s1, s1, -8
	s_sub_i32 s0, s0, s1
	s_cmp_lt_i32 s0, 0
	s_cselect_b32 s1, s22, s21
	s_mul_i32 s0, s1, s0
	s_add_i32 s0, s0, s14
	s_ashr_i32 s1, s0, 31
	s_lshr_b32 s1, s1, 27
	s_add_i32 s1, s0, s1
	s_ashr_i32 s14, s1, 5
	s_lshl_b32 s14, s14, 3
	s_sub_i32 s15, s27, s14
	s_min_i32 s15, s15, 8
	s_abs_i32 s16, s15
	v_cvt_f32_u32_e32 v2, s16
	s_sub_i32 s33, 0, s16
	s_andn2_b32 s1, s1, 31
	s_sub_i32 s0, s0, s1
	v_rcp_iflag_f32_e32 v2, v2
	s_abs_i32 s1, s0
	s_xor_b32 s17, s0, s15
	s_ashr_i32 s17, s17, 31
	v_mul_f32_e32 v2, 0x4f7ffffe, v2
	v_cvt_u32_f32_e32 v2, v2
	s_nop 0
	v_readfirstlane_b32 s35, v2
	s_mul_i32 s33, s33, s35
	s_mul_hi_u32 s33, s35, s33
	s_add_i32 s35, s35, s33
	s_mul_hi_u32 s33, s1, s35
	s_mul_i32 s35, s33, s16
	s_sub_i32 s1, s1, s35
	s_add_i32 s36, s33, 1
	s_sub_i32 s35, s1, s16
	s_cmp_ge_u32 s1, s16
	s_cselect_b32 s33, s36, s33
	s_cselect_b32 s1, s35, s1
	s_add_i32 s35, s33, 1
	s_cmp_ge_u32 s1, s16
	s_cselect_b32 s1, s35, s33
	s_xor_b32 s1, s1, s17
	s_sub_i32 s35, s1, s17
	s_mul_i32 s1, s35, s15
	s_sub_i32 s0, s0, s1
	s_add_i32 s36, s0, s14
